# retention output phase: V tile requested at the top of the unit; state fragments of the cross-chunk MFMAs read two k-slices ahead with counted waits
# baseline (speedup 1.0000x reference)
.LBB0_659:
	v_mov_b32_e32 v165, v160
	s_movk_i32 s8, 0x110
	v_lshlrev_b32_e32 v166, 4, v165
	v_and_b32_e32 v0, 0xf0, v166
	v_add_u32_e32 v0, 0, v0
	v_lshrrev_b32_e32 v1, 4, v165
	v_add_u32_e32 v167, 0x200, v165
	v_mad_u64_u32 v[2:3], s[6:7], v1, s8, v[0:1]
	v_lshrrev_b32_e32 v1, 4, v167
	v_add_u32_e32 v168, 0x400, v165
	s_ashr_i32 s2, s92, 9
	s_ashr_i32 s3, s2, 31
	s_lshl_b64 s[20:21], s[2:3], 13
	s_lshl_b32 s5, s92, 7
	s_and_b32 s5, s5, 0x1f80
	s_or_b32 s20, s20, s5
	s_mul_i32 s2, s21, 0x3000
	s_mul_hi_u32 s3, s20, 0x3000
	s_add_i32 s3, s3, s2
	s_mul_i32 s2, s20, 0x3000
	s_add_u32 s2, s14, s2
	s_addc_u32 s3, s15, s3
	s_lshl_b32 s34, s4, 7
	s_lshl_b32 s54, s4, 8
	s_add_u32 s24, s2, s54
	s_addc_u32 s25, s3, 0
	v_lshlrev_b32_e32 v180, 3, v165
	v_and_b32_e32 v180, 0xf8, v180
	v_add_u32_e32 v180, s34, v180
	v_or_b32_e32 v180, 0x800, v180
	v_lshrrev_b32_e32 v181, 5, v165
	v_mul_u32_u24_e32 v181, 0x1800, v181
	v_add_lshl_u32 v180, v180, v181, 1
	global_load_dwordx4 v[68:71], v180, s[24:25]
	s_add_u32 s20, s24, 0x30000
	s_addc_u32 s21, s25, 0
	global_load_dwordx4 v[64:67], v180, s[20:21]
	s_add_u32 s20, s20, 0x30000
	s_addc_u32 s21, s21, 0
	global_load_dwordx4 v[76:79], v180, s[20:21]
	s_add_u32 s20, s20, 0x30000
	s_addc_u32 s21, s21, 0
	global_load_dwordx4 v[72:75], v180, s[20:21]
	s_add_u32 s20, s20, 0x30000
	s_addc_u32 s21, s21, 0
	global_load_dwordx4 v[148:151], v180, s[20:21]
	s_add_u32 s20, s20, 0x30000
	s_addc_u32 s21, s21, 0
	global_load_dwordx4 v[144:147], v180, s[20:21]
	s_add_u32 s20, s20, 0x30000
	s_addc_u32 s21, s21, 0
	global_load_dwordx4 v[156:159], v180, s[20:21]
	s_add_u32 s20, s20, 0x30000
	s_addc_u32 s21, s21, 0
	global_load_dwordx4 v[152:155], v180, s[20:21]
	s_barrier
	s_waitcnt vmcnt(23)
	ds_write_b128 v2, v[80:83]
	v_mad_u64_u32 v[2:3], s[6:7], v1, s8, v[0:1]
	v_lshrrev_b32_e32 v1, 4, v168
	v_add_u32_e32 v169, 0x600, v165
	s_waitcnt vmcnt(22)
	ds_write_b128 v2, v[84:87]
	v_mad_u64_u32 v[2:3], s[6:7], v1, s8, v[0:1]
	v_lshrrev_b32_e32 v1, 4, v169
	v_mad_u64_u32 v[0:1], s[6:7], v1, s8, v[0:1]
	s_waitcnt vmcnt(21)
	ds_write_b128 v2, v[88:91]
	s_waitcnt vmcnt(20)
	ds_write_b128 v0, v[92:95]
	v_lshlrev_b32_e32 v0, 5, v165
	v_and_b32_e32 v0, 0xe0, v0
	v_add_u32_e32 v8, 0, v0
	s_waitcnt vmcnt(19)
	v_cvt_pk_f32_fp8_e32 v[0:1], v96
	v_cvt_pk_f32_fp8_sdwa v[2:3], v96 src0_sel:WORD_1
	v_cvt_pk_f32_fp8_e32 v[4:5], v97
	v_cvt_pk_f32_fp8_sdwa v[6:7], v97 src0_sel:WORD_1
	v_cvt_pk_bf16_f32 v0, v0, v1
	v_cvt_pk_bf16_f32 v1, v2, v3
	v_cvt_pk_bf16_f32 v2, v4, v5
	v_cvt_pk_bf16_f32 v3, v6, v7
	v_cvt_pk_f32_fp8_e32 v[4:5], v98
	v_cvt_pk_f32_fp8_sdwa v[6:7], v98 src0_sel:WORD_1
	v_cvt_pk_f32_fp8_e32 v[10:11], v99
	v_cvt_pk_f32_fp8_sdwa v[12:13], v99 src0_sel:WORD_1
	s_ashr_i32 s2, s92, 9
	s_ashr_i32 s3, s2, 31
	v_lshrrev_b32_e32 v9, 3, v165
	s_lshl_b64 s[20:21], s[2:3], 13
	v_cvt_pk_bf16_f32 v4, v4, v5
	v_cvt_pk_bf16_f32 v5, v6, v7
	v_cvt_pk_bf16_f32 v6, v10, v11
	v_cvt_pk_bf16_f32 v7, v12, v13
	v_mad_u64_u32 v[10:11], s[2:3], v9, s8, v[8:9]
	ds_write_b128 v10, v[0:3] offset:34816
	ds_write_b128 v10, v[4:7] offset:34832
	s_waitcnt vmcnt(18)
	v_cvt_pk_f32_fp8_e32 v[0:1], v100
	v_cvt_pk_f32_fp8_sdwa v[2:3], v100 src0_sel:WORD_1
	v_cvt_pk_f32_fp8_e32 v[4:5], v101
	v_cvt_pk_f32_fp8_sdwa v[6:7], v101 src0_sel:WORD_1
	v_cvt_pk_bf16_f32 v0, v0, v1
	v_cvt_pk_bf16_f32 v1, v2, v3
	v_cvt_pk_bf16_f32 v2, v4, v5
	v_cvt_pk_bf16_f32 v3, v6, v7
	v_cvt_pk_f32_fp8_e32 v[4:5], v102
	v_cvt_pk_f32_fp8_sdwa v[6:7], v102 src0_sel:WORD_1
	v_cvt_pk_f32_fp8_e32 v[10:11], v103
	v_cvt_pk_f32_fp8_sdwa v[12:13], v103 src0_sel:WORD_1
	v_lshrrev_b32_e32 v9, 3, v167
	v_cvt_pk_bf16_f32 v4, v4, v5
	v_cvt_pk_bf16_f32 v5, v6, v7
	v_cvt_pk_bf16_f32 v6, v10, v11
	v_cvt_pk_bf16_f32 v7, v12, v13
	v_mad_u64_u32 v[10:11], s[2:3], v9, s8, v[8:9]
	ds_write_b128 v10, v[0:3] offset:34816
	ds_write_b128 v10, v[4:7] offset:34832
	s_waitcnt vmcnt(17)
	v_cvt_pk_f32_fp8_e32 v[0:1], v104
	v_cvt_pk_f32_fp8_sdwa v[2:3], v104 src0_sel:WORD_1
	v_cvt_pk_f32_fp8_e32 v[4:5], v105
	v_cvt_pk_f32_fp8_sdwa v[6:7], v105 src0_sel:WORD_1
	v_cvt_pk_bf16_f32 v0, v0, v1
	v_cvt_pk_bf16_f32 v1, v2, v3
	v_cvt_pk_bf16_f32 v2, v4, v5
	v_cvt_pk_bf16_f32 v3, v6, v7
	v_cvt_pk_f32_fp8_e32 v[4:5], v106
	v_cvt_pk_f32_fp8_sdwa v[6:7], v106 src0_sel:WORD_1
	v_cvt_pk_f32_fp8_e32 v[10:11], v107
	v_cvt_pk_f32_fp8_sdwa v[12:13], v107 src0_sel:WORD_1
	v_lshrrev_b32_e32 v9, 3, v168
	v_cvt_pk_bf16_f32 v4, v4, v5
	v_cvt_pk_bf16_f32 v5, v6, v7
	v_cvt_pk_bf16_f32 v6, v10, v11
	v_cvt_pk_bf16_f32 v7, v12, v13
	v_mad_u64_u32 v[10:11], s[2:3], v9, s8, v[8:9]
	ds_write_b128 v10, v[0:3] offset:34816
	ds_write_b128 v10, v[4:7] offset:34832
	s_waitcnt vmcnt(16)
	v_cvt_pk_f32_fp8_e32 v[0:1], v108
	v_cvt_pk_f32_fp8_sdwa v[2:3], v108 src0_sel:WORD_1
	v_cvt_pk_f32_fp8_e32 v[4:5], v109
	v_cvt_pk_f32_fp8_sdwa v[6:7], v109 src0_sel:WORD_1
	s_lshl_b32 s5, s92, 7
	s_and_b32 s5, s5, 0x1f80
	v_cvt_pk_bf16_f32 v0, v0, v1
	v_cvt_pk_bf16_f32 v1, v2, v3
	v_cvt_pk_bf16_f32 v2, v4, v5
	v_cvt_pk_bf16_f32 v3, v6, v7
	v_cvt_pk_f32_fp8_e32 v[4:5], v110
	v_cvt_pk_f32_fp8_sdwa v[6:7], v110 src0_sel:WORD_1
	v_cvt_pk_f32_fp8_e32 v[10:11], v111
	v_cvt_pk_f32_fp8_sdwa v[12:13], v111 src0_sel:WORD_1
	v_lshrrev_b32_e32 v9, 3, v169
	s_or_b32 s20, s20, s5
	v_mad_u64_u32 v[8:9], s[2:3], v9, s8, v[8:9]
	s_mul_i32 s2, s21, 0x3000
	s_mul_hi_u32 s3, s20, 0x3000
	s_add_i32 s3, s3, s2
	s_mul_i32 s2, s20, 0x3000
	v_cvt_pk_bf16_f32 v4, v4, v5
	v_cvt_pk_bf16_f32 v5, v6, v7
	v_cvt_pk_bf16_f32 v6, v10, v11
	v_cvt_pk_bf16_f32 v7, v12, v13
	ds_write_b128 v8, v[0:3] offset:34816
	ds_write_b128 v8, v[4:7] offset:34832
	s_add_u32 s2, s14, s2
	v_lshlrev_b32_e32 v0, 3, v165
	s_addc_u32 s3, s15, s3
	s_lshl_b32 s34, s4, 7
	v_and_b32_e32 v0, 0xf8, v0
	s_lshl_b32 s54, s4, 8
	v_add_u32_e32 v0, s34, v0
	s_add_u32 s24, s2, s54
	v_or_b32_e32 v36, 0x800, v0
	v_lshrrev_b32_e32 v0, 5, v165
	s_movk_i32 s4, 0x1800
	s_addc_u32 s25, s3, 0
	v_mad_u64_u32 v[0:1], s[2:3], v0, s4, v[36:37]
	v_lshrrev_b32_e32 v2, 5, v167
	v_mov_b32_e32 v1, v213
	v_mad_u64_u32 v[2:3], s[2:3], v2, s4, v[36:37]
	v_lshl_add_u64 v[0:1], v[0:1], 1, s[24:25]
	v_mov_b32_e32 v3, v213
	s_waitcnt lgkmcnt(0)
	s_barrier
	v_lshl_add_u64 v[2:3], v[2:3], 1, s[24:25]
	v_lshrrev_b32_e32 v0, 5, v168
	v_mad_u64_u32 v[0:1], s[2:3], v0, s4, v[36:37]
	v_lshrrev_b32_e32 v2, 5, v169
	v_mov_b32_e32 v1, v213
	v_mad_u64_u32 v[2:3], s[2:3], v2, s4, v[36:37]
	v_lshl_add_u64 v[0:1], v[0:1], 1, s[24:25]
	v_mov_b32_e32 v3, v213
	v_add_u32_e32 v171, 0x800, v165
	v_lshl_add_u64 v[2:3], v[2:3], 1, s[24:25]
	v_lshrrev_b32_e32 v0, 5, v171
	v_mad_u64_u32 v[0:1], s[2:3], v0, s4, v[36:37]
	v_mov_b32_e32 v1, v213
	v_add_u32_e32 v172, 0xa00, v165
	v_add_u32_e32 v190, 0xc00, v165
	v_and_b32_e32 v163, 31, v165
	v_lshl_add_u64 v[4:5], v[0:1], 1, s[24:25]
	v_lshrrev_b32_e32 v0, 5, v172
	v_lshrrev_b32_e32 v20, 5, v190
	v_add_u32_e32 v191, 0xe00, v165
	v_bfe_u32 v162, v165, 5, 1
	v_mad_u64_u32 v[6:7], s[2:3], v0, s4, v[36:37]
	v_or_b32_e32 v0, s29, v163
	v_mad_u64_u32 v[20:21], s[2:3], v20, s4, v[36:37]
	v_lshrrev_b32_e32 v37, 5, v191
	v_lshlrev_b32_e32 v170, 4, v162
	v_mul_lo_u32 v0, v0, s8
	v_mov_b32_e32 v21, v213
	v_mad_u64_u32 v[36:37], s[2:3], v37, s4, v[36:37]
	v_mov_b32_e32 v7, v213
	v_add3_u32 v178, 0, v170, v0
	v_lshl_add_u64 v[52:53], v[20:21], 1, s[24:25]
	v_mov_b32_e32 v37, v213
	ds_read_b128 v[0:3], v178 offset:34816
	v_lshl_add_u64 v[6:7], v[6:7], 1, s[24:25]
	ds_read_b128 v[16:19], v178 offset:43520
	ds_read_b128 v[32:35], v178 offset:52224
	v_lshl_add_u64 v[54:55], v[36:37], 1, s[24:25]
	ds_read_b128 v[48:51], v178 offset:60928
	ds_read_b128 v[174:177], v178 offset:34848
	ds_read_b128 v[180:183], v178 offset:43552
	ds_read_b128 v[184:187], v178 offset:52256
	ds_read_b128 v[192:195], v178 offset:60960
	s_waitcnt vmcnt(15) lgkmcnt(7)
	v_mfma_f32_32x32x16_bf16 v[0:15], v[112:115], v[0:3], 0
	v_and_b32_e32 v164, 63, v165
	v_and_b32_e32 v173, 16, v165
	s_waitcnt lgkmcnt(6)
	v_mfma_f32_32x32x16_bf16 v[16:31], v[112:115], v[16:19], 0
	s_waitcnt lgkmcnt(5)
	v_mfma_f32_32x32x16_bf16 v[32:47], v[112:115], v[32:35], 0
	s_waitcnt lgkmcnt(4)
	v_mfma_f32_32x32x16_bf16 v[48:63], v[112:115], v[48:51], 0
	ds_read_b128 v[196:199], v178 offset:34880
	ds_read_b128 v[200:203], v178 offset:43584
	ds_read_b128 v[204:207], v178 offset:52288
	ds_read_b128 v[208:211], v178 offset:60992
	s_waitcnt vmcnt(14) lgkmcnt(7)
	v_mfma_f32_32x32x16_bf16 v[0:15], v[116:119], v[174:177], v[0:15]
	ds_read_b128 v[174:177], v178 offset:34912
	s_waitcnt lgkmcnt(7)
	v_mfma_f32_32x32x16_bf16 v[16:31], v[116:119], v[180:183], v[16:31]
	ds_read_b128 v[180:183], v178 offset:43616
	s_waitcnt lgkmcnt(7)
	v_mfma_f32_32x32x16_bf16 v[32:47], v[116:119], v[184:187], v[32:47]
	ds_read_b128 v[184:187], v178 offset:52320
	s_waitcnt lgkmcnt(7)
	v_mfma_f32_32x32x16_bf16 v[48:63], v[116:119], v[192:195], v[48:63]
	ds_read_b128 v[192:195], v178 offset:61024
	s_waitcnt vmcnt(13) lgkmcnt(7)
	v_mfma_f32_32x32x16_bf16 v[0:15], v[120:123], v[196:199], v[0:15]
	ds_read_b128 v[196:199], v178 offset:34944
	s_waitcnt lgkmcnt(7)
	v_mfma_f32_32x32x16_bf16 v[16:31], v[120:123], v[200:203], v[16:31]
	ds_read_b128 v[200:203], v178 offset:43648
	s_waitcnt lgkmcnt(7)
	v_mfma_f32_32x32x16_bf16 v[32:47], v[120:123], v[204:207], v[32:47]
	ds_read_b128 v[204:207], v178 offset:52352
	s_waitcnt lgkmcnt(7)
	v_mfma_f32_32x32x16_bf16 v[48:63], v[120:123], v[208:211], v[48:63]
	ds_read_b128 v[208:211], v178 offset:61056
	s_waitcnt vmcnt(12) lgkmcnt(7)
	v_mfma_f32_32x32x16_bf16 v[0:15], v[124:127], v[174:177], v[0:15]
	ds_read_b128 v[174:177], v178 offset:34976
	s_waitcnt lgkmcnt(7)
	v_mfma_f32_32x32x16_bf16 v[16:31], v[124:127], v[180:183], v[16:31]
	ds_read_b128 v[180:183], v178 offset:43680
	s_waitcnt lgkmcnt(7)
	v_mfma_f32_32x32x16_bf16 v[32:47], v[124:127], v[184:187], v[32:47]
	ds_read_b128 v[184:187], v178 offset:52384
	s_waitcnt lgkmcnt(7)
	v_mfma_f32_32x32x16_bf16 v[48:63], v[124:127], v[192:195], v[48:63]
	ds_read_b128 v[192:195], v178 offset:61088
	s_waitcnt vmcnt(11) lgkmcnt(7)
	v_mfma_f32_32x32x16_bf16 v[0:15], v[128:131], v[196:199], v[0:15]
	ds_read_b128 v[196:199], v178 offset:35008
	s_waitcnt lgkmcnt(7)
	v_mfma_f32_32x32x16_bf16 v[16:31], v[128:131], v[200:203], v[16:31]
	ds_read_b128 v[200:203], v178 offset:43712
	s_waitcnt lgkmcnt(7)
	v_mfma_f32_32x32x16_bf16 v[32:47], v[128:131], v[204:207], v[32:47]
	ds_read_b128 v[204:207], v178 offset:52416
	s_waitcnt lgkmcnt(7)
	v_mfma_f32_32x32x16_bf16 v[48:63], v[128:131], v[208:211], v[48:63]
	ds_read_b128 v[208:211], v178 offset:61120
	s_waitcnt vmcnt(10) lgkmcnt(7)
	v_mfma_f32_32x32x16_bf16 v[0:15], v[132:135], v[174:177], v[0:15]
	ds_read_b128 v[174:177], v178 offset:35040
	s_waitcnt lgkmcnt(7)
	v_mfma_f32_32x32x16_bf16 v[16:31], v[132:135], v[180:183], v[16:31]
	ds_read_b128 v[180:183], v178 offset:43744
	s_waitcnt lgkmcnt(7)
	v_mfma_f32_32x32x16_bf16 v[32:47], v[132:135], v[184:187], v[32:47]
	ds_read_b128 v[184:187], v178 offset:52448
	s_waitcnt lgkmcnt(7)
	v_mfma_f32_32x32x16_bf16 v[48:63], v[132:135], v[192:195], v[48:63]
	ds_read_b128 v[192:195], v178 offset:61152
	s_waitcnt vmcnt(9) lgkmcnt(7)
	v_mfma_f32_32x32x16_bf16 v[0:15], v[136:139], v[196:199], v[0:15]
	s_waitcnt lgkmcnt(6)
	v_mfma_f32_32x32x16_bf16 v[16:31], v[136:139], v[200:203], v[16:31]
	s_waitcnt lgkmcnt(5)
	v_mfma_f32_32x32x16_bf16 v[32:47], v[136:139], v[204:207], v[32:47]
	s_waitcnt lgkmcnt(4)
	v_mfma_f32_32x32x16_bf16 v[48:63], v[136:139], v[208:211], v[48:63]
	s_waitcnt vmcnt(8) lgkmcnt(3)
	v_mfma_f32_32x32x16_bf16 v[0:15], v[140:143], v[174:177], v[0:15]
	s_waitcnt lgkmcnt(2)
	v_mfma_f32_32x32x16_bf16 v[16:31], v[140:143], v[180:183], v[16:31]
	s_waitcnt lgkmcnt(1)
	v_mfma_f32_32x32x16_bf16 v[32:47], v[140:143], v[184:187], v[32:47]
	s_waitcnt lgkmcnt(0)
	v_mfma_f32_32x32x16_bf16 v[48:63], v[140:143], v[192:195], v[48:63]
	v_lshl_or_b32 v189, v162, 2, s28
	v_or_b32_e32 v174, 1, v189
	v_or_b32_e32 v175, 2, v189
	v_cvt_f32_ubyte0_e32 v174, v174
	v_cvt_f32_ubyte0_e32 v175, v175
	v_mul_f32_e32 v174, v161, v174
	v_mul_f32_e32 v175, v161, v175
	v_or_b32_e32 v176, 3, v189
	v_add_u32_e32 v177, 4, v189
	v_or_b32_e32 v178, 9, v189
	v_or_b32_e32 v179, 10, v189
	v_or_b32_e32 v180, 11, v189
	v_add_u32_e32 v181, 12, v189
	v_or_b32_e32 v182, 17, v189
	v_or_b32_e32 v183, 18, v189
	v_or_b32_e32 v184, 19, v189
	v_add_u32_e32 v185, 20, v189
	v_or_b32_e32 v186, 25, v189
	v_or_b32_e32 v187, 26, v189
	v_or_b32_e32 v188, 27, v189
	v_add_u32_e32 v189, 28, v189
	v_exp_f32_e32 v174, v174
	v_exp_f32_e32 v175, v175
	v_cvt_f32_ubyte0_e32 v176, v176
	v_cvt_f32_ubyte0_e32 v177, v177
	v_cvt_f32_ubyte0_e32 v178, v178
	v_cvt_f32_ubyte0_e32 v179, v179
	v_cvt_f32_ubyte0_e32 v180, v180
	v_cvt_f32_ubyte0_e32 v181, v181
	v_cvt_f32_ubyte0_e32 v182, v182
	v_cvt_f32_ubyte0_e32 v183, v183
	v_cvt_f32_ubyte0_e32 v184, v184
	v_cvt_f32_ubyte0_e32 v185, v185
	v_cvt_f32_ubyte0_e32 v186, v186
	v_cvt_f32_ubyte0_e32 v187, v187
	v_cvt_f32_ubyte0_e32 v188, v188
	v_cvt_f32_ubyte0_e32 v189, v189
	v_mul_f32_e32 v176, v161, v176
	v_mul_f32_e32 v177, v161, v177
	v_mul_f32_e32 v178, v161, v178
	v_mul_f32_e32 v179, v161, v179
	v_mul_f32_e32 v180, v161, v180
	v_mul_f32_e32 v181, v161, v181
	v_mul_f32_e32 v182, v161, v182
	v_mul_f32_e32 v183, v161, v183
	v_mul_f32_e32 v184, v161, v184
	v_mul_f32_e32 v185, v161, v185
	v_mul_f32_e32 v186, v161, v186
	v_mul_f32_e32 v187, v161, v187
	v_mul_f32_e32 v188, v161, v188
	v_mul_f32_e32 v189, v161, v189
	v_exp_f32_e32 v176, v176
	v_exp_f32_e32 v177, v177
	v_exp_f32_e32 v178, v178
	v_exp_f32_e32 v179, v179
	v_exp_f32_e32 v180, v180
	v_exp_f32_e32 v181, v181
	v_exp_f32_e32 v182, v182
	v_exp_f32_e32 v183, v183
	v_exp_f32_e32 v184, v184
	v_exp_f32_e32 v185, v185
	v_exp_f32_e32 v186, v186
	v_exp_f32_e32 v187, v187
	v_exp_f32_e32 v188, v188
	v_exp_f32_e32 v189, v189
	s_mov_b32 s2, 0x3e800000
	v_pk_mul_f32 v[174:175], v[174:175], s[2:3] op_sel_hi:[1,0]
	v_and_b32_e32 v166, 0x1f0, v166
	v_pk_mul_f32 v[0:1], v[174:175], v[0:1]
	v_pk_mul_f32 v[16:17], v[174:175], v[16:17]
	v_pk_mul_f32 v[32:33], v[174:175], v[32:33]
	v_pk_mul_f32 v[48:49], v[174:175], v[48:49]
	v_add_u32_e32 v166, 0, v166
	v_ashrrev_i32_e32 v174, 5, v165
	s_movk_i32 s4, 0x210
	v_pk_mul_f32 v[176:177], v[176:177], s[2:3] op_sel_hi:[1,0]
	v_pk_mul_f32 v[178:179], v[178:179], s[2:3] op_sel_hi:[1,0]
	v_pk_mul_f32 v[180:181], v[180:181], s[2:3] op_sel_hi:[1,0]
	v_pk_mul_f32 v[182:183], v[182:183], s[2:3] op_sel_hi:[1,0]
	v_pk_mul_f32 v[184:185], v[184:185], s[2:3] op_sel_hi:[1,0]
	v_pk_mul_f32 v[186:187], v[186:187], s[2:3] op_sel_hi:[1,0]
	v_pk_mul_f32 v[188:189], v[188:189], s[2:3] op_sel_hi:[1,0]
	v_mad_u64_u32 v[174:175], s[2:3], v174, s4, v[166:167]
	s_barrier
	s_waitcnt vmcnt(7)
	ds_write_b128 v174, v[68:71] offset:34816
	v_ashrrev_i32_e32 v68, 5, v167
	v_mad_u64_u32 v[68:69], s[2:3], v68, s4, v[166:167]
	s_waitcnt vmcnt(6)
	ds_write_b128 v68, v[64:67] offset:34816
	v_ashrrev_i32_e32 v64, 5, v168
	v_mad_u64_u32 v[64:65], s[2:3], v64, s4, v[166:167]
	s_waitcnt vmcnt(5)
	ds_write_b128 v64, v[76:79] offset:34816
	v_ashrrev_i32_e32 v64, 5, v169
	v_mad_u64_u32 v[64:65], s[2:3], v64, s4, v[166:167]
	s_waitcnt vmcnt(4)
	ds_write_b128 v64, v[72:75] offset:34816
	v_ashrrev_i32_e32 v64, 5, v171
	v_mad_u64_u32 v[64:65], s[2:3], v64, s4, v[166:167]
	s_waitcnt vmcnt(3)
	ds_write_b128 v64, v[148:151] offset:34816
	v_ashrrev_i32_e32 v64, 5, v172
	v_mad_u64_u32 v[64:65], s[2:3], v64, s4, v[166:167]
	s_waitcnt vmcnt(2)
	ds_write_b128 v64, v[144:147] offset:34816
	v_ashrrev_i32_e32 v64, 5, v190
	v_mad_u64_u32 v[64:65], s[2:3], v64, s4, v[166:167]
	s_waitcnt vmcnt(1)
	ds_write_b128 v64, v[156:159] offset:34816
	v_ashrrev_i32_e32 v64, 5, v191
	v_mad_u64_u32 v[64:65], s[2:3], v64, s4, v[166:167]
	v_not_b32_e32 v66, 16
	s_waitcnt vmcnt(0)
	ds_write_b128 v64, v[152:155] offset:34816
	v_mad_i32_i24 v153, v162, -4, v66
	v_not_b32_e32 v66, 18
	v_mad_i32_i24 v155, v162, -4, v66
	v_not_b32_e32 v66, 17
	v_mad_i32_i24 v154, v162, -4, v66
	v_not_b32_e32 v66, 24
	v_mad_i32_i24 v157, v162, -4, v66
	v_not_b32_e32 v66, 23
	v_lshlrev_b32_e32 v65, 2, v165
	v_mad_i32_i24 v156, v162, -4, v66
	v_not_b32_e32 v66, 26
	v_bfe_u32 v64, v165, 2, 2
	v_and_b32_e32 v65, 12, v65
	v_mad_i32_i24 v159, v162, -4, v66
	v_not_b32_e32 v66, 25
	v_add_u32_e32 v67, s29, v173
	v_mad_i32_i24 v158, v162, -4, v66
	v_mul_u32_u24_e32 v66, 0x840, v162
	v_mul_u32_u24_e32 v64, 0x210, v64
	v_add_lshl_u32 v65, v67, v65, 1
	v_pk_mul_f32 v[14:15], v[188:189], v[14:15]
	v_pk_mul_f32 v[12:13], v[186:187], v[12:13]
	v_pk_mul_f32 v[10:11], v[184:185], v[10:11]
	v_pk_mul_f32 v[8:9], v[182:183], v[8:9]
	v_pk_mul_f32 v[6:7], v[180:181], v[6:7]
	v_pk_mul_f32 v[4:5], v[178:179], v[4:5]
	v_pk_mul_f32 v[2:3], v[176:177], v[2:3]
	v_pk_mul_f32 v[30:31], v[188:189], v[30:31]
	v_pk_mul_f32 v[28:29], v[186:187], v[28:29]
	v_pk_mul_f32 v[26:27], v[184:185], v[26:27]
	v_pk_mul_f32 v[24:25], v[182:183], v[24:25]
	v_pk_mul_f32 v[22:23], v[180:181], v[22:23]
	v_pk_mul_f32 v[20:21], v[178:179], v[20:21]
	v_pk_mul_f32 v[18:19], v[176:177], v[18:19]
	v_pk_mul_f32 v[46:47], v[188:189], v[46:47]
	v_pk_mul_f32 v[44:45], v[186:187], v[44:45]
	v_pk_mul_f32 v[42:43], v[184:185], v[42:43]
	v_pk_mul_f32 v[40:41], v[182:183], v[40:41]
	v_pk_mul_f32 v[38:39], v[180:181], v[38:39]
	v_pk_mul_f32 v[36:37], v[178:179], v[36:37]
	v_pk_mul_f32 v[34:35], v[176:177], v[34:35]
	v_pk_mul_f32 v[62:63], v[188:189], v[62:63]
	v_pk_mul_f32 v[60:61], v[186:187], v[60:61]
	v_pk_mul_f32 v[58:59], v[184:185], v[58:59]
	v_pk_mul_f32 v[56:57], v[182:183], v[56:57]
	v_pk_mul_f32 v[54:55], v[180:181], v[54:55]
	v_pk_mul_f32 v[52:53], v[178:179], v[52:53]
	v_pk_mul_f32 v[50:51], v[176:177], v[50:51]
	v_mul_i32_i24_e32 v144, -4, v162
	v_mad_i32_i24 v145, v162, -4, -1
	v_mad_i32_i24 v147, v162, -4, -3
	v_mad_i32_i24 v146, v162, -4, -2
	v_mad_i32_i24 v149, v162, -4, -9
	v_mad_i32_i24 v148, v162, -4, -8
	v_mad_i32_i24 v151, v162, -4, -11
	v_mad_i32_i24 v150, v162, -4, -10
	v_mad_i32_i24 v152, v162, -4, -16
	v_add3_u32 v165, v66, v64, v65
	v_mad_u32_u24 v166, v163, s8, v170
	s_mov_b32 s35, s28
	s_waitcnt lgkmcnt(0)
	s_barrier
